# dense attention finalize: O stores widened with v_permlane32_swap pairs (dwordx2 -> dwordx4)
# speedup vs baseline: 1.0074x; 1.0074x over previous
.LBB0_1012:
	s_ashr_i32 s39, s0, 7
	s_lshl_b32 s4, s0, 9
	s_bfe_u32 s1, s0, 0x40003
	s_and_b32 s40, s4, 0xe00
	s_lshl_b32 s4, s39, 4
	s_or_b32 s4, s4, s1
	s_add_i32 s40, s40, s38
	s_ashr_i32 s5, s4, 31
	s_lshr_b32 s6, s0, 3
	s_lshl_b64 s[4:5], s[4:5], 12
	s_ashr_i32 s7, s40, 31
	s_add_u32 s4, s4, s40
	s_addc_u32 s5, s5, s7
	v_mov_b32_e32 v1, s5
	v_or_b32_e32 v0, s4, v202
	s_bfe_u32 s4, s6, 0x20002
	s_lshl_b32 s5, s39, 2
	s_or_b32 s4, s4, s5
	v_lshlrev_b64 v[0:1], 7, v[0:1]
	s_ashr_i32 s5, s4, 31
	v_lshl_add_u64 v[2:3], v[204:205], 0, v[0:1]
	v_or_b32_e32 v0, 0x1000, v0
	s_lshl_b64 s[4:5], s[4:5], 19
	v_lshl_add_u64 v[0:1], v[204:205], 0, v[0:1]
	v_lshl_add_u64 v[212:213], v[208:209], 0, s[4:5]
	global_load_dwordx4 v[130:133], v[2:3], off
	global_load_dwordx4 v[134:137], v[2:3], off offset:32
	global_load_dwordx4 v[138:141], v[2:3], off offset:64
	global_load_dwordx4 v[142:145], v[2:3], off offset:96
	global_load_dwordx4 v[146:149], v[0:1], off
	global_load_dwordx4 v[150:153], v[0:1], off offset:32
	global_load_dwordx4 v[154:157], v[0:1], off offset:64
	global_load_dwordx4 v[158:161], v[0:1], off offset:96
	v_lshl_add_u64 v[214:215], v[210:211], 0, s[4:5]
	global_load_dwordx4 v[0:3], v[212:213], off
	global_load_dwordx4 v[4:7], v[214:215], off
	s_mov_b64 s[6:7], 0x2000
	v_lshl_add_u64 v[182:183], v[212:213], 0, s[6:7]
	global_load_dwordx4 v[182:185], v[182:183], off
	global_load_dwordx4 v[178:181], v[214:215], off offset:128
	v_mov_b32_e32 v82, 0xf149f2ca
	s_mov_b32 s4, 0
	s_movk_i32 s42, 0x6c00
	s_movk_i32 s41, 0x4800
	s_mov_b32 s5, 0x9000
	v_mov_b32_e32 v162, 0
	v_mov_b32_e32 v163, 0
	v_mov_b32_e32 v164, 0
	v_mov_b32_e32 v165, 0
	v_mov_b32_e32 v174, 0
	v_mov_b32_e32 v175, 0
	v_mov_b32_e32 v176, 0
	v_mov_b32_e32 v177, 0
	v_mov_b32_e32 v166, 0
	v_mov_b32_e32 v167, 0
	v_mov_b32_e32 v168, 0
	v_mov_b32_e32 v169, 0
	v_mov_b32_e32 v170, 0
	v_mov_b32_e32 v171, 0
	v_mov_b32_e32 v172, 0
	v_mov_b32_e32 v173, 0
	v_mov_b32_e32 v83, v82
	v_mov_b32_e32 v84, v82
	v_mov_b32_e32 v85, v82
	v_mov_b32_e32 v86, v82
	v_mov_b32_e32 v87, v82
	v_mov_b32_e32 v88, v82
	v_mov_b32_e32 v89, v82
	v_mov_b32_e32 v90, v82
	v_mov_b32_e32 v91, v82
	v_mov_b32_e32 v92, v82
	v_mov_b32_e32 v93, v82
	v_mov_b32_e32 v94, v82
	v_mov_b32_e32 v95, v82
	v_mov_b32_e32 v96, v82
	v_mov_b32_e32 v97, v82
	v_mov_b32_e32 v66, v82
	v_mov_b32_e32 v67, v82
	v_mov_b32_e32 v68, v82
	v_mov_b32_e32 v69, v82
	v_mov_b32_e32 v70, v82
	v_mov_b32_e32 v71, v82
	v_mov_b32_e32 v72, v82
	v_mov_b32_e32 v73, v82
	v_mov_b32_e32 v74, v82
	v_mov_b32_e32 v75, v82
	v_mov_b32_e32 v76, v82
	v_mov_b32_e32 v77, v82
	v_mov_b32_e32 v78, v82
	v_mov_b32_e32 v79, v82
	v_mov_b32_e32 v80, v82
	v_mov_b32_e32 v81, v82
	s_waitcnt vmcnt(3)
	ds_write_b128 v203, v[0:3]
	s_waitcnt vmcnt(2)
	ds_write_b128 v203, v[4:7] offset:18432
	v_mov_b32_e32 v0, 0
	v_mov_b32_e32 v1, v0
	v_mov_b32_e32 v2, v0
	v_mov_b32_e32 v3, v0
	v_mov_b32_e32 v4, v0
	v_mov_b32_e32 v5, v0
	v_mov_b32_e32 v6, v0
	v_mov_b32_e32 v7, v0
	v_mov_b32_e32 v8, v0
	v_mov_b32_e32 v9, v0
	v_mov_b32_e32 v10, v0
	v_mov_b32_e32 v11, v0
	v_mov_b32_e32 v12, v0
	v_mov_b32_e32 v13, v0
	v_mov_b32_e32 v14, v0
	v_mov_b32_e32 v15, v0
	v_mov_b32_e32 v16, v0
	v_mov_b32_e32 v17, v0
	v_mov_b32_e32 v18, v0
	v_mov_b32_e32 v19, v0
	v_mov_b32_e32 v20, v0
	v_mov_b32_e32 v21, v0
	v_mov_b32_e32 v22, v0
	v_mov_b32_e32 v23, v0
	v_mov_b32_e32 v24, v0
	v_mov_b32_e32 v25, v0
	v_mov_b32_e32 v26, v0
	v_mov_b32_e32 v27, v0
	v_mov_b32_e32 v28, v0
	v_mov_b32_e32 v29, v0
	v_mov_b32_e32 v30, v0
	v_mov_b32_e32 v31, v0
	v_mov_b32_e32 v34, v0
	v_mov_b32_e32 v35, v0
	v_mov_b32_e32 v36, v0
	v_mov_b32_e32 v37, v0
	v_mov_b32_e32 v38, v0
	v_mov_b32_e32 v39, v0
	v_mov_b32_e32 v40, v0
	v_mov_b32_e32 v41, v0
	v_mov_b32_e32 v42, v0
	v_mov_b32_e32 v43, v0
	v_mov_b32_e32 v44, v0
	v_mov_b32_e32 v45, v0
	v_mov_b32_e32 v46, v0
	v_mov_b32_e32 v47, v0
	v_mov_b32_e32 v48, v0
	v_mov_b32_e32 v49, v0
	v_mov_b32_e32 v50, v0
	v_mov_b32_e32 v51, v0
	v_mov_b32_e32 v52, v0
	v_mov_b32_e32 v53, v0
	v_mov_b32_e32 v54, v0
	v_mov_b32_e32 v55, v0
	v_mov_b32_e32 v56, v0
	v_mov_b32_e32 v57, v0
	v_mov_b32_e32 v58, v0
	v_mov_b32_e32 v59, v0
	v_mov_b32_e32 v60, v0
	v_mov_b32_e32 v61, v0
	v_mov_b32_e32 v62, v0
	v_mov_b32_e32 v63, v0
	v_mov_b32_e32 v64, v0
	v_mov_b32_e32 v65, v0
	v_mov_b32_e32 v216, v0
	v_mov_b32_e32 v217, v0
	s_waitcnt lgkmcnt(0)
	s_barrier
	v_mov_b32_e32 v234, v245
	v_add_u32_e32 v235, s5, v32
	s_cmpk_lt_u32 s38, 0x100
	s_cselect_b32 s101, 0, 1
	v_mov_b32_e32 v186, 0
	v_mov_b32_e32 v187, 0
	v_mov_b32_e32 v188, 0
	v_mov_b32_e32 v189, 0
	v_mov_b32_e32 v190, 0
	v_mov_b32_e32 v191, 0
	v_mov_b32_e32 v192, 0
	v_mov_b32_e32 v193, 0
	v_mov_b32_e32 v218, 0
	v_mov_b32_e32 v219, 0
	v_mov_b32_e32 v220, 0
	v_mov_b32_e32 v221, 0
	v_mov_b32_e32 v222, 0
	v_mov_b32_e32 v223, 0
	v_mov_b32_e32 v224, 0
	v_mov_b32_e32 v225, 0
	ds_read_b128 v[226:229], v235
	ds_read_b128 v[230:233], v235 offset:4608
	s_cmp_eq_u32 s101, 0
	s_cbranch_scc1 .Lpp_enter
	s_barrier
	s_nop 0

.Lpp_exit:
	s_setprio 0
	v_exp_f32_e32 v82, v82
	v_exp_f32_e32 v83, v83
	v_exp_f32_e32 v84, v84
	v_exp_f32_e32 v85, v85
	v_add_f32_e32 v98, 0, v82
	v_exp_f32_e32 v99, v86
	v_add_f32_e32 v98, v83, v98
	v_add_f32_e32 v98, v84, v98
	v_add_f32_e32 v98, v85, v98
	v_add_f32_e32 v86, v99, v98
	v_exp_f32_e32 v98, v87
	v_exp_f32_e32 v100, v88
	v_exp_f32_e32 v89, v89
	v_exp_f32_e32 v101, v90
	v_add_f32_e32 v86, v98, v86
	v_exp_f32_e32 v91, v91
	v_add_f32_e32 v86, v100, v86
	v_exp_f32_e32 v92, v92
	v_add_f32_e32 v86, v89, v86
	v_exp_f32_e32 v93, v93
	v_add_f32_e32 v86, v101, v86
	v_exp_f32_e32 v94, v94
	v_add_f32_e32 v86, v91, v86
	v_exp_f32_e32 v95, v95
	v_add_f32_e32 v86, v92, v86
	v_exp_f32_e32 v96, v96
	v_add_f32_e32 v86, v93, v86
	v_exp_f32_e32 v97, v97
	v_add_f32_e32 v86, v94, v86
	v_exp_f32_e32 v66, v66
	v_add_f32_e32 v86, v95, v86
	v_exp_f32_e32 v67, v67
	v_add_f32_e32 v86, v96, v86
	v_exp_f32_e32 v68, v68
	v_add_f32_e32 v86, v97, v86
	v_exp_f32_e32 v69, v69
	v_add_f32_e32 v90, v217, v86
	v_cvt_pk_bf16_f32 v86, v82, v83
	v_cvt_pk_bf16_f32 v82, v101, v91
	v_cvt_pk_bf16_f32 v83, v92, v93
	v_add_f32_e32 v91, 0, v66
	v_exp_f32_e32 v92, v70
	v_add_f32_e32 v91, v67, v91
	v_add_f32_e32 v91, v68, v91
	v_add_f32_e32 v91, v69, v91
	v_add_f32_e32 v70, v92, v91
	v_exp_f32_e32 v91, v71
	v_exp_f32_e32 v93, v72
	v_exp_f32_e32 v73, v73
	v_cvt_pk_bf16_f32 v87, v84, v85
	v_cvt_pk_bf16_f32 v84, v94, v95
	v_exp_f32_e32 v94, v74
	v_add_f32_e32 v70, v91, v70
	v_exp_f32_e32 v75, v75
	v_add_f32_e32 v70, v93, v70
	v_exp_f32_e32 v76, v76
	v_add_f32_e32 v70, v73, v70
	v_exp_f32_e32 v77, v77
	v_add_f32_e32 v70, v94, v70
	v_exp_f32_e32 v78, v78
	v_add_f32_e32 v70, v75, v70
	v_exp_f32_e32 v79, v79
	v_add_f32_e32 v70, v76, v70
	v_exp_f32_e32 v80, v80
	v_add_f32_e32 v70, v77, v70
	v_exp_f32_e32 v81, v81
	v_add_f32_e32 v70, v78, v70
	v_add_f32_e32 v70, v79, v70
	v_add_f32_e32 v70, v80, v70
	v_add_f32_e32 v70, v81, v70
	v_add_f32_e32 v74, v216, v70
	v_cvt_pk_bf16_f32 v70, v66, v67
	v_cvt_pk_bf16_f32 v71, v68, v69
	v_cvt_pk_bf16_f32 v72, v92, v91
	v_cvt_pk_bf16_f32 v73, v93, v73
	v_cvt_pk_bf16_f32 v66, v94, v75
	v_cvt_pk_bf16_f32 v67, v76, v77
	v_cvt_pk_bf16_f32 v68, v78, v79
	ds_read_b128 v[76:79], v32 offset:18432
	ds_read_b128 v[92:95], v32 offset:18464
	s_waitcnt lgkmcnt(1)
	v_mfma_f32_32x32x16_bf16 v[50:65], v[76:79], v[170:173], v[50:65]
	v_cvt_pk_bf16_f32 v88, v99, v98
	v_cvt_pk_bf16_f32 v89, v100, v89
	v_cvt_pk_bf16_f32 v85, v96, v97
	v_cvt_pk_bf16_f32 v69, v80, v81
	s_lshl_b32 s4, s39, 12
	s_add_i32 s40, s40, s4
	s_lshl_b32 s16, s1, 7
	v_mfma_f32_32x32x16_bf16 v[16:31], v[76:79], v[174:177], v[16:31]
	ds_read_b128 v[76:79], v32 offset:23040
	s_add_i32 s0, s0, s78
	s_cmpk_gt_i32 s0, 0x3ff
	s_waitcnt lgkmcnt(0)
	v_mfma_f32_32x32x16_bf16 v[34:49], v[76:79], v[170:173], v[34:49]
	v_mfma_f32_32x32x16_bf16 v[0:15], v[76:79], v[174:177], v[0:15]
	ds_read_b128 v[76:79], v32 offset:23072
	s_waitcnt lgkmcnt(0)
	v_mfma_f32_32x32x16_bf16 v[34:49], v[76:79], v[166:169], v[34:49]
	v_mfma_f32_32x32x16_bf16 v[0:15], v[76:79], v[162:165], v[0:15]
	ds_read_b128 v[76:79], v32 offset:18496
	v_mfma_f32_32x32x16_bf16 v[50:65], v[92:95], v[166:169], v[50:65]
	v_mfma_f32_32x32x16_bf16 v[16:31], v[92:95], v[162:165], v[16:31]
	s_waitcnt lgkmcnt(0)
	v_mfma_f32_32x32x16_bf16 v[50:65], v[76:79], v[86:89], v[50:65]
	v_mfma_f32_32x32x16_bf16 v[16:31], v[76:79], v[70:73], v[16:31]
	ds_read_b128 v[76:79], v32 offset:23104
	s_waitcnt lgkmcnt(0)
	v_mfma_f32_32x32x16_bf16 v[0:15], v[76:79], v[70:73], v[0:15]
	ds_read_b128 v[70:73], v32 offset:18528
	s_waitcnt lgkmcnt(0)
	v_mfma_f32_32x32x16_bf16 v[50:65], v[70:73], v[82:85], v[50:65]
	v_mfma_f32_32x32x16_bf16 v[16:31], v[70:73], v[66:69], v[16:31]
	ds_read_b128 v[70:73], v32 offset:23136
	s_waitcnt lgkmcnt(0)
	s_barrier
	v_mfma_f32_32x32x16_bf16 v[34:49], v[76:79], v[86:89], v[34:49]
	v_mfma_f32_32x32x16_bf16 v[0:15], v[70:73], v[66:69], v[0:15]
	ds_bpermute_b32 v69, v244, v90
	v_or_b32_e32 v68, s40, v202
	v_lshl_add_u64 v[66:67], v[206:207], 0, s[16:17]
	s_waitcnt lgkmcnt(0)
	v_add_f32_e32 v69, v90, v69
	v_mfma_f32_32x32x16_bf16 v[34:49], v[70:73], v[82:85], v[34:49]
	v_div_scale_f32 v70, s[4:5], v69, v69, 1.0
	v_rcp_f32_e32 v71, v70
	s_nop 0
	v_fma_f32 v72, -v70, v71, 1.0
	v_fmac_f32_e32 v71, v72, v71
	v_div_scale_f32 v72, vcc, 1.0, v69, 1.0
	v_mul_f32_e32 v73, v72, v71
	v_fma_f32 v75, -v70, v73, v72
	v_fmac_f32_e32 v73, v75, v71
	v_fma_f32 v70, -v70, v73, v72
	v_div_fmas_f32 v70, v70, v71, v73
	v_div_fixup_f32 v70, v70, v69, 1.0
	v_ashrrev_i32_e32 v69, 31, v68
	v_lshlrev_b64 v[72:73], 11, v[68:69]
	v_lshl_add_u64 v[72:73], v[66:67], 0, v[72:73]
	v_mbcnt_lo_u32_b32 v116, -1, 0
	v_mbcnt_hi_u32_b32 v116, -1, v116
	ds_bpermute_b32 v108, v244, v74
	v_and_b32_e32 v116, 32, v116
	v_lshrrev_b32_e32 v116, 2, v116
	v_mov_b32_e32 v117, 0
	v_or_b32_e32 v114, 32, v68
	v_ashrrev_i32_e32 v115, 31, v114
	v_lshlrev_b64 v[114:115], 11, v[114:115]
	v_lshl_add_u64 v[72:73], v[72:73], 0, v[116:117]
	v_lshl_add_u64 v[114:115], v[66:67], 0, v[114:115]
	v_lshl_add_u64 v[114:115], v[114:115], 0, v[116:117]
	v_pk_mul_f32 v[50:51], v[50:51], v[70:71] op_sel_hi:[1,0]
	v_pk_mul_f32 v[52:53], v[52:53], v[70:71] op_sel_hi:[1,0]
	v_pk_mul_f32 v[54:55], v[54:55], v[70:71] op_sel_hi:[1,0]
	v_pk_mul_f32 v[56:57], v[56:57], v[70:71] op_sel_hi:[1,0]
	v_cvt_pk_bf16_f32 v76, v50, v51
	v_cvt_pk_bf16_f32 v77, v52, v53
	v_cvt_pk_bf16_f32 v78, v54, v55
	v_cvt_pk_bf16_f32 v79, v56, v57
	s_nop 1
	v_permlane32_swap_b32 v76, v78
	v_permlane32_swap_b32 v77, v79
	global_store_dwordx4 v[72:73], v[76:79], off
	v_pk_mul_f32 v[58:59], v[58:59], v[70:71] op_sel_hi:[1,0]
	v_pk_mul_f32 v[60:61], v[60:61], v[70:71] op_sel_hi:[1,0]
	v_pk_mul_f32 v[62:63], v[62:63], v[70:71] op_sel_hi:[1,0]
	v_pk_mul_f32 v[64:65], v[64:65], v[70:71] op_sel_hi:[1,0]
	v_cvt_pk_bf16_f32 v80, v58, v59
	v_cvt_pk_bf16_f32 v81, v60, v61
	v_cvt_pk_bf16_f32 v82, v62, v63
	v_cvt_pk_bf16_f32 v83, v64, v65
	s_nop 1
	v_permlane32_swap_b32 v80, v82
	v_permlane32_swap_b32 v81, v83
	global_store_dwordx4 v[72:73], v[80:83], off offset:32
	s_waitcnt lgkmcnt(0)
	v_add_f32_e32 v108, v74, v108
	v_div_scale_f32 v109, s[4:5], v108, v108, 1.0
	v_rcp_f32_e32 v110, v109
	s_nop 0
	v_fma_f32 v111, -v109, v110, 1.0
	v_fmac_f32_e32 v110, v111, v110
	v_div_scale_f32 v111, vcc, 1.0, v108, 1.0
	v_mul_f32_e32 v112, v111, v110
	v_fma_f32 v113, -v109, v112, v111
	v_fmac_f32_e32 v112, v113, v110
	v_fma_f32 v109, -v109, v112, v111
	v_div_fmas_f32 v109, v109, v110, v112
	v_div_fixup_f32 v108, v109, v108, 1.0
	v_pk_mul_f32 v[34:35], v[34:35], v[70:71] op_sel_hi:[1,0]
	v_pk_mul_f32 v[36:37], v[36:37], v[70:71] op_sel_hi:[1,0]
	v_pk_mul_f32 v[38:39], v[38:39], v[70:71] op_sel_hi:[1,0]
	v_pk_mul_f32 v[40:41], v[40:41], v[70:71] op_sel_hi:[1,0]
	v_cvt_pk_bf16_f32 v84, v34, v35
	v_cvt_pk_bf16_f32 v85, v36, v37
	v_cvt_pk_bf16_f32 v86, v38, v39
	v_cvt_pk_bf16_f32 v87, v40, v41
	s_nop 1
	v_permlane32_swap_b32 v84, v86
	v_permlane32_swap_b32 v85, v87
	global_store_dwordx4 v[72:73], v[84:87], off offset:64
	v_pk_mul_f32 v[42:43], v[42:43], v[70:71] op_sel_hi:[1,0]
	v_pk_mul_f32 v[44:45], v[44:45], v[70:71] op_sel_hi:[1,0]
	v_pk_mul_f32 v[46:47], v[46:47], v[70:71] op_sel_hi:[1,0]
	v_pk_mul_f32 v[48:49], v[48:49], v[70:71] op_sel_hi:[1,0]
	v_cvt_pk_bf16_f32 v88, v42, v43
	v_cvt_pk_bf16_f32 v89, v44, v45
	v_cvt_pk_bf16_f32 v90, v46, v47
	v_cvt_pk_bf16_f32 v91, v48, v49
	s_nop 1
	v_permlane32_swap_b32 v88, v90
	v_permlane32_swap_b32 v89, v91
	global_store_dwordx4 v[72:73], v[88:91], off offset:96
	v_pk_mul_f32 v[16:17], v[16:17], v[108:109] op_sel_hi:[1,0]
	v_pk_mul_f32 v[18:19], v[18:19], v[108:109] op_sel_hi:[1,0]
	v_pk_mul_f32 v[20:21], v[20:21], v[108:109] op_sel_hi:[1,0]
	v_pk_mul_f32 v[22:23], v[22:23], v[108:109] op_sel_hi:[1,0]
	v_cvt_pk_bf16_f32 v92, v16, v17
	v_cvt_pk_bf16_f32 v93, v18, v19
	v_cvt_pk_bf16_f32 v94, v20, v21
	v_cvt_pk_bf16_f32 v95, v22, v23
	s_nop 1
	v_permlane32_swap_b32 v92, v94
	v_permlane32_swap_b32 v93, v95
	global_store_dwordx4 v[114:115], v[92:95], off
	v_pk_mul_f32 v[24:25], v[24:25], v[108:109] op_sel_hi:[1,0]
	v_pk_mul_f32 v[26:27], v[26:27], v[108:109] op_sel_hi:[1,0]
	v_pk_mul_f32 v[28:29], v[28:29], v[108:109] op_sel_hi:[1,0]
	v_pk_mul_f32 v[30:31], v[30:31], v[108:109] op_sel_hi:[1,0]
	v_cvt_pk_bf16_f32 v96, v24, v25
	v_cvt_pk_bf16_f32 v97, v26, v27
	v_cvt_pk_bf16_f32 v98, v28, v29
	v_cvt_pk_bf16_f32 v99, v30, v31
	s_nop 1
	v_permlane32_swap_b32 v96, v98
	v_permlane32_swap_b32 v97, v99
	global_store_dwordx4 v[114:115], v[96:99], off offset:32
	v_pk_mul_f32 v[0:1], v[0:1], v[108:109] op_sel_hi:[1,0]
	v_pk_mul_f32 v[2:3], v[2:3], v[108:109] op_sel_hi:[1,0]
	v_pk_mul_f32 v[4:5], v[4:5], v[108:109] op_sel_hi:[1,0]
	v_pk_mul_f32 v[6:7], v[6:7], v[108:109] op_sel_hi:[1,0]
	v_cvt_pk_bf16_f32 v100, v0, v1
	v_cvt_pk_bf16_f32 v101, v2, v3
	v_cvt_pk_bf16_f32 v102, v4, v5
	v_cvt_pk_bf16_f32 v103, v6, v7
	s_nop 1
	v_permlane32_swap_b32 v100, v102
	v_permlane32_swap_b32 v101, v103
	global_store_dwordx4 v[114:115], v[100:103], off offset:64
	v_pk_mul_f32 v[8:9], v[8:9], v[108:109] op_sel_hi:[1,0]
	v_pk_mul_f32 v[10:11], v[10:11], v[108:109] op_sel_hi:[1,0]
	v_pk_mul_f32 v[12:13], v[12:13], v[108:109] op_sel_hi:[1,0]
	v_pk_mul_f32 v[14:15], v[14:15], v[108:109] op_sel_hi:[1,0]
	v_cvt_pk_bf16_f32 v104, v8, v9
	v_cvt_pk_bf16_f32 v105, v10, v11
	v_cvt_pk_bf16_f32 v106, v12, v13
	v_cvt_pk_bf16_f32 v107, v14, v15
	s_nop 1
	v_permlane32_swap_b32 v104, v106
	v_permlane32_swap_b32 v105, v107
	global_store_dwordx4 v[114:115], v[104:107], off offset:96
	s_cbranch_scc0 .LBB0_1012
	v_mov_b32_e32 v246, 0x60
	v_mov_b64_e32 v[248:249], 0x300
	v_mov_b64_e32 v[250:251], 0x2ff
